# V pass: A-set table prefetch loads issued spread through the B compute block (unconditional, drained at exit) instead of one burst
# baseline (speedup 1.0000x reference)
.LBB0_933:
	s_and_b32 s101, s59, 3
	v_lshl_add_u32 v253, s101, 8, v252
	ds_read_b32 v212, v253
	ds_read_b32 v213, v253 offset:1024
	v_cvt_pk_f32_fp8_e32 v[222:223], v124
	v_cvt_pk_f32_fp8_sdwa v[224:225], v124 src0_sel:WORD_1
	global_load_dwordx4 v[0:3], v0, s[14:15]
	v_cvt_pk_f32_fp8_e32 v[226:227], v125
	v_cvt_pk_f32_fp8_sdwa v[124:125], v125 src0_sel:WORD_1
	v_lshl_add_u32 v128, s59, 9, v193
	v_cvt_pk_f32_fp8_e32 v[234:235], v120
	v_cvt_pk_f32_fp8_sdwa v[236:237], v120 src0_sel:WORD_1
	v_cvt_pk_f32_fp8_e32 v[238:239], v121
	v_cvt_pk_f32_fp8_sdwa v[120:121], v121 src0_sel:WORD_1
	ds_read_b128 v[132:135], v128
	ds_read_b128 v[214:217], v128 offset:16
	ds_read_b128 v[218:221], v128 offset:32
	ds_read_b128 v[128:131], v128 offset:48
	v_cvt_pk_f32_fp8_e32 v[228:229], v126
	global_load_dwordx4 v[4:7], v4, s[14:15]
	s_waitcnt lgkmcnt(3)
	v_pk_fma_f32 v[222:223], v[132:133], v[222:223], 0 op_sel_hi:[0,1,0]
	v_pk_fma_f32 v[224:225], v[132:133], v[224:225], 0 op_sel_hi:[0,1,0]
	v_pk_fma_f32 v[124:125], v[132:133], v[124:125], 0 op_sel_hi:[0,1,0]
	v_cvt_pk_f32_fp8_sdwa v[230:231], v126 src0_sel:WORD_1
	v_cvt_pk_f32_fp8_e32 v[232:233], v127
	v_cvt_pk_f32_fp8_sdwa v[126:127], v127 src0_sel:WORD_1
	v_pk_fma_f32 v[222:223], v[132:133], v[234:235], v[222:223] op_sel:[1,0,0]
	v_pk_fma_f32 v[224:225], v[132:133], v[236:237], v[224:225] op_sel:[1,0,0]
	v_pk_fma_f32 v[120:121], v[132:133], v[120:121], v[124:125] op_sel:[1,0,0]
	v_cvt_pk_f32_fp8_e32 v[124:125], v122
	v_cvt_pk_f32_fp8_sdwa v[234:235], v122 src0_sel:WORD_1
	v_cvt_pk_f32_fp8_e32 v[236:237], v123
	global_load_dwordx4 v[8:11], v8, s[14:15]
	v_cvt_pk_f32_fp8_sdwa v[122:123], v123 src0_sel:WORD_1
	v_pk_fma_f32 v[226:227], v[132:133], v[226:227], 0 op_sel_hi:[0,1,0]
	v_pk_fma_f32 v[228:229], v[132:133], v[228:229], 0 op_sel_hi:[0,1,0]
	v_pk_fma_f32 v[230:231], v[132:133], v[230:231], 0 op_sel_hi:[0,1,0]
	v_pk_fma_f32 v[232:233], v[132:133], v[232:233], 0 op_sel_hi:[0,1,0]
	v_pk_fma_f32 v[126:127], v[132:133], v[126:127], 0 op_sel_hi:[0,1,0]
	v_pk_fma_f32 v[226:227], v[132:133], v[238:239], v[226:227] op_sel:[1,0,0]
	v_pk_fma_f32 v[124:125], v[132:133], v[124:125], v[228:229] op_sel:[1,0,0]
	v_pk_fma_f32 v[228:229], v[132:133], v[234:235], v[230:231] op_sel:[1,0,0]
	v_pk_fma_f32 v[230:231], v[132:133], v[236:237], v[232:233] op_sel:[1,0,0]
	v_pk_fma_f32 v[122:123], v[132:133], v[122:123], v[126:127] op_sel:[1,0,0]
	v_cvt_pk_f32_fp8_e32 v[126:127], v116
	v_cvt_pk_f32_fp8_sdwa v[132:133], v116 src0_sel:WORD_1
	global_load_dwordx4 v[12:15], v12, s[14:15]
	v_cvt_pk_f32_fp8_e32 v[232:233], v117
	v_cvt_pk_f32_fp8_sdwa v[116:117], v117 src0_sel:WORD_1
	v_pk_fma_f32 v[126:127], v[134:135], v[126:127], v[222:223] op_sel_hi:[0,1,1]
	v_pk_fma_f32 v[132:133], v[134:135], v[132:133], v[224:225] op_sel_hi:[0,1,1]
	v_pk_fma_f32 v[222:223], v[134:135], v[232:233], v[226:227] op_sel_hi:[0,1,1]
	v_pk_fma_f32 v[116:117], v[134:135], v[116:117], v[120:121] op_sel_hi:[0,1,1]
	v_cvt_pk_f32_fp8_e32 v[120:121], v118
	v_cvt_pk_f32_fp8_sdwa v[224:225], v118 src0_sel:WORD_1
	v_cvt_pk_f32_fp8_e32 v[226:227], v119
	v_cvt_pk_f32_fp8_sdwa v[118:119], v119 src0_sel:WORD_1
	v_pk_fma_f32 v[120:121], v[134:135], v[120:121], v[124:125] op_sel_hi:[0,1,1]
	v_pk_fma_f32 v[124:125], v[134:135], v[224:225], v[228:229] op_sel_hi:[0,1,1]
	global_load_dwordx4 v[16:19], v16, s[14:15]
	v_pk_fma_f32 v[224:225], v[134:135], v[226:227], v[230:231] op_sel_hi:[0,1,1]
	v_pk_fma_f32 v[118:119], v[134:135], v[118:119], v[122:123] op_sel_hi:[0,1,1]
	v_mov_b32_e32 v122, v135
	v_cvt_pk_f32_fp8_e32 v[134:135], v112
	v_cvt_pk_f32_fp8_sdwa v[226:227], v112 src0_sel:WORD_1
	v_cvt_pk_f32_fp8_e32 v[228:229], v113
	v_cvt_pk_f32_fp8_sdwa v[112:113], v113 src0_sel:WORD_1
	v_pk_fma_f32 v[126:127], v[122:123], v[134:135], v[126:127] op_sel_hi:[0,1,1]
	v_pk_fma_f32 v[132:133], v[122:123], v[226:227], v[132:133] op_sel_hi:[0,1,1]
	v_pk_fma_f32 v[134:135], v[122:123], v[228:229], v[222:223] op_sel_hi:[0,1,1]
	v_pk_fma_f32 v[112:113], v[122:123], v[112:113], v[116:117] op_sel_hi:[0,1,1]
	v_cvt_pk_f32_fp8_e32 v[116:117], v114
	v_cvt_pk_f32_fp8_sdwa v[222:223], v114 src0_sel:WORD_1
	global_load_dwordx4 v[20:23], v20, s[14:15]
	v_cvt_pk_f32_fp8_e32 v[226:227], v115
	v_cvt_pk_f32_fp8_sdwa v[114:115], v115 src0_sel:WORD_1
	v_pk_fma_f32 v[116:117], v[122:123], v[116:117], v[120:121] op_sel_hi:[0,1,1]
	v_pk_fma_f32 v[120:121], v[122:123], v[222:223], v[124:125] op_sel_hi:[0,1,1]
	v_pk_fma_f32 v[124:125], v[122:123], v[226:227], v[224:225] op_sel_hi:[0,1,1]
	v_pk_fma_f32 v[114:115], v[122:123], v[114:115], v[118:119] op_sel_hi:[0,1,1]
	v_cvt_pk_f32_fp8_e32 v[118:119], v108
	v_cvt_pk_f32_fp8_sdwa v[122:123], v108 src0_sel:WORD_1
	v_cvt_pk_f32_fp8_e32 v[222:223], v109
	v_cvt_pk_f32_fp8_sdwa v[108:109], v109 src0_sel:WORD_1
	s_waitcnt lgkmcnt(2)
	v_pk_fma_f32 v[118:119], v[214:215], v[118:119], v[126:127] op_sel_hi:[0,1,1]
	v_pk_fma_f32 v[122:123], v[214:215], v[122:123], v[132:133] op_sel_hi:[0,1,1]
	global_load_dwordx4 v[24:27], v24, s[14:15]
	v_pk_fma_f32 v[126:127], v[214:215], v[222:223], v[134:135] op_sel_hi:[0,1,1]
	v_pk_fma_f32 v[108:109], v[214:215], v[108:109], v[112:113] op_sel_hi:[0,1,1]
	v_cvt_pk_f32_fp8_e32 v[112:113], v110
	v_cvt_pk_f32_fp8_sdwa v[132:133], v110 src0_sel:WORD_1
	v_cvt_pk_f32_fp8_e32 v[134:135], v111
	v_cvt_pk_f32_fp8_sdwa v[110:111], v111 src0_sel:WORD_1
	v_pk_fma_f32 v[112:113], v[214:215], v[112:113], v[116:117] op_sel_hi:[0,1,1]
	v_pk_fma_f32 v[116:117], v[214:215], v[132:133], v[120:121] op_sel_hi:[0,1,1]
	v_pk_fma_f32 v[120:121], v[214:215], v[134:135], v[124:125] op_sel_hi:[0,1,1]
	v_pk_fma_f32 v[110:111], v[214:215], v[110:111], v[114:115] op_sel_hi:[0,1,1]
	v_cvt_pk_f32_fp8_e32 v[114:115], v104
	v_cvt_pk_f32_fp8_sdwa v[124:125], v104 src0_sel:WORD_1
	global_load_dwordx4 v[28:31], v28, s[14:15]
	v_cvt_pk_f32_fp8_e32 v[132:133], v105
	v_cvt_pk_f32_fp8_sdwa v[104:105], v105 src0_sel:WORD_1
	v_pk_fma_f32 v[114:115], v[214:215], v[114:115], v[118:119] op_sel:[1,0,0]
	v_pk_fma_f32 v[118:119], v[214:215], v[124:125], v[122:123] op_sel:[1,0,0]
	v_pk_fma_f32 v[122:123], v[214:215], v[132:133], v[126:127] op_sel:[1,0,0]
	v_pk_fma_f32 v[104:105], v[214:215], v[104:105], v[108:109] op_sel:[1,0,0]
	v_cvt_pk_f32_fp8_e32 v[108:109], v106
	v_cvt_pk_f32_fp8_sdwa v[124:125], v106 src0_sel:WORD_1
	v_cvt_pk_f32_fp8_e32 v[126:127], v107
	v_cvt_pk_f32_fp8_sdwa v[106:107], v107 src0_sel:WORD_1
	v_pk_fma_f32 v[108:109], v[214:215], v[108:109], v[112:113] op_sel:[1,0,0]
	v_pk_fma_f32 v[112:113], v[214:215], v[124:125], v[116:117] op_sel:[1,0,0]
	v_pk_fma_f32 v[116:117], v[214:215], v[126:127], v[120:121] op_sel:[1,0,0]
	global_load_dwordx4 v[32:35], v32, s[14:15]
	v_pk_fma_f32 v[106:107], v[214:215], v[106:107], v[110:111] op_sel:[1,0,0]
	v_cvt_pk_f32_fp8_e32 v[110:111], v100
	v_cvt_pk_f32_fp8_sdwa v[120:121], v100 src0_sel:WORD_1
	v_cvt_pk_f32_fp8_e32 v[124:125], v101
	v_cvt_pk_f32_fp8_sdwa v[100:101], v101 src0_sel:WORD_1
	v_pk_fma_f32 v[110:111], v[216:217], v[110:111], v[114:115] op_sel_hi:[0,1,1]
	v_pk_fma_f32 v[114:115], v[216:217], v[120:121], v[118:119] op_sel_hi:[0,1,1]
	v_pk_fma_f32 v[118:119], v[216:217], v[124:125], v[122:123] op_sel_hi:[0,1,1]
	v_pk_fma_f32 v[100:101], v[216:217], v[100:101], v[104:105] op_sel_hi:[0,1,1]
	v_cvt_pk_f32_fp8_e32 v[104:105], v102
	v_cvt_pk_f32_fp8_sdwa v[120:121], v102 src0_sel:WORD_1
	v_cvt_pk_f32_fp8_e32 v[122:123], v103
	global_load_dwordx4 v[36:39], v36, s[14:15]
	v_cvt_pk_f32_fp8_sdwa v[102:103], v103 src0_sel:WORD_1
	v_pk_fma_f32 v[104:105], v[216:217], v[104:105], v[108:109] op_sel_hi:[0,1,1]
	v_pk_fma_f32 v[108:109], v[216:217], v[120:121], v[112:113] op_sel_hi:[0,1,1]
	v_pk_fma_f32 v[112:113], v[216:217], v[122:123], v[116:117] op_sel_hi:[0,1,1]
	v_cvt_pk_f32_fp8_e32 v[116:117], v96
	v_cvt_pk_f32_fp8_sdwa v[120:121], v96 src0_sel:WORD_1
	v_cvt_pk_f32_fp8_e32 v[122:123], v97
	v_cvt_pk_f32_fp8_sdwa v[96:97], v97 src0_sel:WORD_1
	v_pk_fma_f32 v[102:103], v[216:217], v[102:103], v[106:107] op_sel_hi:[0,1,1]
	v_mov_b32_e32 v106, v217
	v_pk_fma_f32 v[110:111], v[106:107], v[116:117], v[110:111] op_sel_hi:[0,1,1]
	v_pk_fma_f32 v[114:115], v[106:107], v[120:121], v[114:115] op_sel_hi:[0,1,1]
	v_pk_fma_f32 v[116:117], v[106:107], v[122:123], v[118:119] op_sel_hi:[0,1,1]
	global_load_dwordx4 v[40:43], v40, s[14:15]
	v_pk_fma_f32 v[96:97], v[106:107], v[96:97], v[100:101] op_sel_hi:[0,1,1]
	v_cvt_pk_f32_fp8_e32 v[100:101], v98
	v_cvt_pk_f32_fp8_sdwa v[118:119], v98 src0_sel:WORD_1
	v_cvt_pk_f32_fp8_e32 v[120:121], v99
	v_cvt_pk_f32_fp8_sdwa v[98:99], v99 src0_sel:WORD_1
	v_pk_fma_f32 v[100:101], v[106:107], v[100:101], v[104:105] op_sel_hi:[0,1,1]
	v_pk_fma_f32 v[104:105], v[106:107], v[118:119], v[108:109] op_sel_hi:[0,1,1]
	v_pk_fma_f32 v[108:109], v[106:107], v[120:121], v[112:113] op_sel_hi:[0,1,1]
	v_pk_fma_f32 v[98:99], v[106:107], v[98:99], v[102:103] op_sel_hi:[0,1,1]
	v_cvt_pk_f32_fp8_e32 v[102:103], v92
	v_cvt_pk_f32_fp8_sdwa v[106:107], v92 src0_sel:WORD_1
	v_cvt_pk_f32_fp8_e32 v[112:113], v93
	v_cvt_pk_f32_fp8_sdwa v[92:93], v93 src0_sel:WORD_1
	global_load_dwordx4 v[44:47], v44, s[14:15]
	s_waitcnt lgkmcnt(1)
	v_pk_fma_f32 v[102:103], v[218:219], v[102:103], v[110:111] op_sel_hi:[0,1,1]
	v_pk_fma_f32 v[106:107], v[218:219], v[106:107], v[114:115] op_sel_hi:[0,1,1]
	v_pk_fma_f32 v[110:111], v[218:219], v[112:113], v[116:117] op_sel_hi:[0,1,1]
	v_pk_fma_f32 v[92:93], v[218:219], v[92:93], v[96:97] op_sel_hi:[0,1,1]
	v_cvt_pk_f32_fp8_e32 v[96:97], v94
	v_cvt_pk_f32_fp8_sdwa v[112:113], v94 src0_sel:WORD_1
	v_cvt_pk_f32_fp8_e32 v[114:115], v95
	v_cvt_pk_f32_fp8_sdwa v[94:95], v95 src0_sel:WORD_1
	v_pk_fma_f32 v[96:97], v[218:219], v[96:97], v[100:101] op_sel_hi:[0,1,1]
	v_pk_fma_f32 v[100:101], v[218:219], v[112:113], v[104:105] op_sel_hi:[0,1,1]
	v_pk_fma_f32 v[104:105], v[218:219], v[114:115], v[108:109] op_sel_hi:[0,1,1]
	global_load_dwordx4 v[48:51], v48, s[14:15]
	v_pk_fma_f32 v[94:95], v[218:219], v[94:95], v[98:99] op_sel_hi:[0,1,1]
	v_cvt_pk_f32_fp8_e32 v[98:99], v88
	v_cvt_pk_f32_fp8_sdwa v[108:109], v88 src0_sel:WORD_1
	v_cvt_pk_f32_fp8_e32 v[112:113], v89
	v_cvt_pk_f32_fp8_sdwa v[88:89], v89 src0_sel:WORD_1
	v_pk_fma_f32 v[98:99], v[218:219], v[98:99], v[102:103] op_sel:[1,0,0]
	v_pk_fma_f32 v[102:103], v[218:219], v[108:109], v[106:107] op_sel:[1,0,0]
	v_pk_fma_f32 v[106:107], v[218:219], v[112:113], v[110:111] op_sel:[1,0,0]
	v_pk_fma_f32 v[88:89], v[218:219], v[88:89], v[92:93] op_sel:[1,0,0]
	v_cvt_pk_f32_fp8_e32 v[92:93], v90
	v_cvt_pk_f32_fp8_sdwa v[108:109], v90 src0_sel:WORD_1
	v_cvt_pk_f32_fp8_e32 v[110:111], v91
	v_cvt_pk_f32_fp8_sdwa v[90:91], v91 src0_sel:WORD_1
	global_load_dwordx4 v[52:55], v52, s[14:15]
	v_pk_fma_f32 v[92:93], v[218:219], v[92:93], v[96:97] op_sel:[1,0,0]
	v_pk_fma_f32 v[96:97], v[218:219], v[108:109], v[100:101] op_sel:[1,0,0]
	v_pk_fma_f32 v[100:101], v[218:219], v[110:111], v[104:105] op_sel:[1,0,0]
	v_pk_fma_f32 v[90:91], v[218:219], v[90:91], v[94:95] op_sel:[1,0,0]
	v_cvt_pk_f32_fp8_e32 v[94:95], v84
	v_cvt_pk_f32_fp8_sdwa v[104:105], v84 src0_sel:WORD_1
	v_cvt_pk_f32_fp8_e32 v[108:109], v85
	v_cvt_pk_f32_fp8_sdwa v[84:85], v85 src0_sel:WORD_1
	v_pk_fma_f32 v[94:95], v[220:221], v[94:95], v[98:99] op_sel_hi:[0,1,1]
	v_pk_fma_f32 v[98:99], v[220:221], v[104:105], v[102:103] op_sel_hi:[0,1,1]
	v_pk_fma_f32 v[102:103], v[220:221], v[108:109], v[106:107] op_sel_hi:[0,1,1]
	v_pk_fma_f32 v[84:85], v[220:221], v[84:85], v[88:89] op_sel_hi:[0,1,1]
	v_cvt_pk_f32_fp8_e32 v[88:89], v86
	global_load_dwordx4 v[56:59], v56, s[14:15]
	v_cvt_pk_f32_fp8_sdwa v[104:105], v86 src0_sel:WORD_1
	v_cvt_pk_f32_fp8_e32 v[106:107], v87
	v_cvt_pk_f32_fp8_sdwa v[86:87], v87 src0_sel:WORD_1
	v_pk_fma_f32 v[88:89], v[220:221], v[88:89], v[92:93] op_sel_hi:[0,1,1]
	v_pk_fma_f32 v[92:93], v[220:221], v[104:105], v[96:97] op_sel_hi:[0,1,1]
	v_pk_fma_f32 v[96:97], v[220:221], v[106:107], v[100:101] op_sel_hi:[0,1,1]
	v_cvt_pk_f32_fp8_e32 v[100:101], v80
	v_cvt_pk_f32_fp8_sdwa v[104:105], v80 src0_sel:WORD_1
	v_cvt_pk_f32_fp8_e32 v[106:107], v81
	v_cvt_pk_f32_fp8_sdwa v[80:81], v81 src0_sel:WORD_1
	v_pk_fma_f32 v[86:87], v[220:221], v[86:87], v[90:91] op_sel_hi:[0,1,1]
	v_mov_b32_e32 v90, v221
	global_load_dwordx4 v[60:63], v60, s[14:15]
	v_pk_fma_f32 v[94:95], v[90:91], v[100:101], v[94:95] op_sel_hi:[0,1,1]
	v_pk_fma_f32 v[98:99], v[90:91], v[104:105], v[98:99] op_sel_hi:[0,1,1]
	v_pk_fma_f32 v[100:101], v[90:91], v[106:107], v[102:103] op_sel_hi:[0,1,1]
	v_pk_fma_f32 v[80:81], v[90:91], v[80:81], v[84:85] op_sel_hi:[0,1,1]
	v_cvt_pk_f32_fp8_e32 v[84:85], v82
	v_cvt_pk_f32_fp8_sdwa v[102:103], v82 src0_sel:WORD_1
	v_cvt_pk_f32_fp8_e32 v[104:105], v83
	v_cvt_pk_f32_fp8_sdwa v[82:83], v83 src0_sel:WORD_1
	v_pk_fma_f32 v[84:85], v[90:91], v[84:85], v[88:89] op_sel_hi:[0,1,1]
	v_pk_fma_f32 v[88:89], v[90:91], v[102:103], v[92:93] op_sel_hi:[0,1,1]
	v_pk_fma_f32 v[92:93], v[90:91], v[104:105], v[96:97] op_sel_hi:[0,1,1]
	v_pk_fma_f32 v[82:83], v[90:91], v[82:83], v[86:87] op_sel_hi:[0,1,1]
	v_cvt_pk_f32_fp8_e32 v[86:87], v76
	v_cvt_pk_f32_fp8_sdwa v[90:91], v76 src0_sel:WORD_1
	v_cvt_pk_f32_fp8_e32 v[96:97], v77
	v_cvt_pk_f32_fp8_sdwa v[76:77], v77 src0_sel:WORD_1
	s_waitcnt lgkmcnt(0)
	s_and_b32 s101, s61, 2
	s_cmp_lg_u32 s101, 0
	s_cbranch_scc1 .Lvx_skip
	s_and_b32 s98, s61, 12
	s_lshl_b32 s98, s98, 12
	s_lshr_b32 s101, s61, 4
	s_lshl_b32 s101, s101, 8
	s_add_i32 s98, s98, s101
	v_add_u32_e32 v253, s98, v254
	s_mov_b32 m0, s100
	s_nop 0
	global_load_lds_dwordx4 v253, s[80:81]
	s_add_i32 m0, s100, 0x400
	s_nop 0
	global_load_lds_dwordx4 v253, s[28:29]

.LBB0_936:
	v_cndmask_b32_e64 v131, v133, v131, s[12:13]
	v_cndmask_b32_e64 v130, v132, v130, s[12:13]
	s_waitcnt lgkmcnt(2)
	v_lshlrev_b32_e32 v132, 16, v210
	v_and_b32_e32 v133, 0xffff0000, v210
	v_lshlrev_b32_e32 v134, 16, v211
	v_and_b32_e32 v135, 0xffff0000, v211
	v_readlane_b32 s98, v248, s1
	v_readlane_b32 s99, v249, s1
	v_or_b32_e32 v214, s1, v176
	s_waitcnt lgkmcnt(0)
	v_pk_add_f32 v[128:129], v[130:131], v[128:129]
	ds_bpermute_b32 v128, v250, v128
	ds_bpermute_b32 v129, v250, v129
	v_pk_fma_f32 v[130:131], v[132:133], s[74:75], v[134:135] op_sel_hi:[1,0,1]
	v_ashrrev_i32_e32 v215, 31, v214
	v_pk_add_f32 v[130:131], v[130:131], s[98:99] op_sel_hi:[1,0] neg_lo:[0,1] neg_hi:[0,1]
	s_add_i32 s61, s0, 2
	v_lshlrev_b64 v[214:215], 13, v[214:215]
	v_pk_mul_f32 v[130:131], s[98:99], v[130:131] op_sel:[1,0]
	s_cmpk_gt_u32 s0, 0xfd
	v_lshl_add_u64 v[214:215], s[78:79], 0, v[214:215]
	s_waitcnt vmcnt(0)
	v_pk_fma_f32 v[130:131], v[130:131], v[178:179], v[180:181]
	s_cselect_b64 s[0:1], -1, 0
	v_lshl_add_u64 v[214:215], v[214:215], 0, v[138:139]
	s_waitcnt lgkmcnt(0)
	v_pk_fma_f32 v[128:129], v[130:131], s[74:75], v[128:129] op_sel_hi:[1,0,1]
	s_and_b64 vcc, exec, s[0:1]
	global_store_dwordx2 v[214:215], v[128:129], off nt
	s_and_b32 s15, s17, 0x700
	v_lshl_add_u32 v0, s15, 2, v189
	ds_read_b128 v[6:9], v0
	ds_read_b128 v[22:25], v0 offset:16
	ds_read_b128 v[38:41], v0 offset:32
	ds_read_b128 v[54:57], v0 offset:48
	s_and_b32 s14, s34, 0x3e00000
	s_add_u32 s14, s38, s14
	s_waitcnt lgkmcnt(2)
	s_waitcnt lgkmcnt(1)
	s_waitcnt lgkmcnt(0)
	s_addc_u32 s15, s39, 0
	v_lshl_or_b32 v4, v7, 7, v137
	v_lshl_or_b32 v0, v6, 7, v174
	v_lshl_or_b32 v12, v9, 7, v137
	v_lshl_or_b32 v8, v8, 7, v174
	v_lshl_or_b32 v20, v23, 7, v137
	v_lshl_or_b32 v16, v22, 7, v174
	v_lshl_or_b32 v28, v25, 7, v137
	v_lshl_or_b32 v24, v24, 7, v174
	v_lshl_or_b32 v36, v39, 7, v137
	v_lshl_or_b32 v32, v38, 7, v174
	v_lshl_or_b32 v44, v41, 7, v137
	v_lshl_or_b32 v40, v40, 7, v174
	v_lshl_or_b32 v52, v55, 7, v137
	v_lshl_or_b32 v48, v54, 7, v174
	v_lshl_or_b32 v60, v57, 7, v137
	v_lshl_or_b32 v56, v56, 7, v174
	s_branch .LBB0_933
.LBB0_938:
	s_waitcnt vmcnt(0)
	s_waitcnt vmcnt(19)
	v_lshlrev_b64 v[0:1], 13, v[176:177]
	s_waitcnt vmcnt(9)
	v_lshl_add_u64 v[40:41], v[172:173], 0, v[0:1]
	global_load_dwordx4 v[0:3], v[152:153], off
	global_load_dwordx4 v[4:7], v[152:153], off offset:1024
	global_load_dwordx4 v[8:11], v[154:155], off
	global_load_dwordx4 v[12:15], v[154:155], off offset:1024
	global_load_dwordx4 v[64:67], v[40:41], off nt
	global_load_dwordx4 v[68:71], v[40:41], off offset:1024 nt
	global_load_dwordx4 v[16:19], v[152:153], off offset:2048
	global_load_dwordx4 v[20:23], v[152:153], off offset:3072
	global_load_dwordx4 v[24:27], v[154:155], off offset:2048
	global_load_dwordx4 v[28:31], v[154:155], off offset:3072
	global_load_dwordx4 v[76:79], v[40:41], off offset:2048 nt
	global_load_dwordx4 v[80:83], v[40:41], off offset:3072 nt
	global_load_dwordx4 v[32:35], v[156:157], off
	global_load_dwordx4 v[36:39], v[158:159], off
	v_add_co_u32_e32 v72, vcc, s41, v40
	s_mov_b32 s0, 0
	s_nop 0
	v_addc_co_u32_e32 v73, vcc, 0, v41, vcc
	global_load_dwordx4 v[40:43], v[160:161], off
	global_load_dwordx4 v[44:47], v[162:163], off
	global_load_dwordx4 v[104:107], v[72:73], off nt
	global_load_dwordx4 v[112:115], v[72:73], off offset:1024 nt
	global_load_dwordx4 v[48:51], v[164:165], off
	global_load_dwordx4 v[52:55], v[166:167], off
	global_load_dwordx4 v[56:59], v[168:169], off
	global_load_dwordx4 v[60:63], v[170:171], off
	global_load_dwordx4 v[120:123], v[72:73], off offset:2048 nt
	global_load_dwordx4 v[124:127], v[72:73], off offset:3072 nt
	s_branch .LBB0_940
